# stack + softmax (s_i - m) subtractions packed pairwise (v_pk_add_f32, in place) in both attention phases
# speedup vs baseline: 1.0293x; 1.0293x over previous
.LBB0_392:
	s_nop 10
	v_max3_f32 v24, v0, s38, v1
	v_max3_f32 v24, v24, v2, v3
	v_max3_f32 v24, v24, v4, v5
	v_max3_f32 v24, v24, v6, v7
	v_max3_f32 v24, v24, v8, v9
	v_max3_f32 v24, v24, v10, v11
	v_max3_f32 v24, v24, v12, v13
	v_max3_f32 v24, v24, v14, v15
	v_max3_f32 v24, v24, v32, v33
	v_max3_f32 v24, v24, v34, v35
	v_max3_f32 v24, v24, v36, v37
	v_max3_f32 v24, v24, v38, v39
	v_max3_f32 v24, v24, v40, v41
	v_max3_f32 v24, v24, v42, v43
	v_max3_f32 v24, v24, v44, v45
	v_max3_f32 v24, v24, v46, v47
	ds_bpermute_b32 v25, v238, v24
	s_and_b64 vcc, s[0:1], exec
	s_cselect_b32 s58, s58, 0x63
	s_cmp_lt_u32 s58, 2
	s_waitcnt lgkmcnt(0)
	v_max3_f32 v197, v24, v25, s38
	v_pk_add_f32 v[0:1], v[0:1], v[196:197] op_sel:[0,1] op_sel_hi:[1,1] neg_lo:[0,1] neg_hi:[0,1]
	v_exp_f32_e32 v141, v0
	v_exp_f32_e32 v142, v1
	v_pk_add_f32 v[2:3], v[2:3], v[196:197] op_sel:[0,1] op_sel_hi:[1,1] neg_lo:[0,1] neg_hi:[0,1]
	v_exp_f32_e32 v143, v2
	v_exp_f32_e32 v144, v3
	v_pk_add_f32 v[4:5], v[4:5], v[196:197] op_sel:[0,1] op_sel_hi:[1,1] neg_lo:[0,1] neg_hi:[0,1]
	v_exp_f32_e32 v145, v4
	v_exp_f32_e32 v146, v5
	v_pk_add_f32 v[6:7], v[6:7], v[196:197] op_sel:[0,1] op_sel_hi:[1,1] neg_lo:[0,1] neg_hi:[0,1]
	v_exp_f32_e32 v147, v6
	v_exp_f32_e32 v148, v7
	v_pk_add_f32 v[8:9], v[8:9], v[196:197] op_sel:[0,1] op_sel_hi:[1,1] neg_lo:[0,1] neg_hi:[0,1]
	v_exp_f32_e32 v149, v8
	v_exp_f32_e32 v150, v9
	v_pk_add_f32 v[10:11], v[10:11], v[196:197] op_sel:[0,1] op_sel_hi:[1,1] neg_lo:[0,1] neg_hi:[0,1]
	v_exp_f32_e32 v151, v10
	v_exp_f32_e32 v152, v11
	v_pk_add_f32 v[12:13], v[12:13], v[196:197] op_sel:[0,1] op_sel_hi:[1,1] neg_lo:[0,1] neg_hi:[0,1]
	v_exp_f32_e32 v153, v12
	v_sub_f32_e32 v24, 0xff800000, v197
	v_exp_f32_e32 v154, v13
	v_pk_add_f32 v[14:15], v[14:15], v[196:197] op_sel:[0,1] op_sel_hi:[1,1] neg_lo:[0,1] neg_hi:[0,1]
	v_exp_f32_e32 v140, v24
	v_exp_f32_e32 v155, v14
	v_cvt_pk_bf16_f32 v24, v141, v142
	v_cvt_pk_bf16_f32 v25, v143, v144
	v_cvt_pk_bf16_f32 v26, v145, v146
	v_cvt_pk_bf16_f32 v27, v147, v148
	v_exp_f32_e32 v156, v15
	v_cvt_pk_bf16_f32 v136, v149, v150
	v_mfma_f32_32x32x16_bf16 v[0:15], v[20:23], v[24:27], 0
	v_cvt_pk_bf16_f32 v137, v151, v152
	v_cvt_pk_bf16_f32 v138, v153, v154
	v_cvt_pk_bf16_f32 v139, v155, v156
	v_pk_add_f32 v[32:33], v[32:33], v[196:197] op_sel:[0,1] op_sel_hi:[1,1] neg_lo:[0,1] neg_hi:[0,1]
	v_fmac_f32_e32 v141, 0, v140
	v_mfma_f32_32x32x16_bf16 v[16:31], v[16:19], v[24:27], 0
	v_mfma_f32_32x32x16_bf16 v[16:31], v[128:131], v[136:139], v[16:31]
	v_exp_f32_e32 v129, v32
	v_exp_f32_e32 v130, v33
	v_pk_add_f32 v[34:35], v[34:35], v[196:197] op_sel:[0,1] op_sel_hi:[1,1] neg_lo:[0,1] neg_hi:[0,1]
	v_exp_f32_e32 v131, v34
	v_add_f32_e32 v128, v142, v141
	v_mfma_f32_32x32x16_bf16 v[0:15], v[132:135], v[136:139], v[0:15]
	v_exp_f32_e32 v132, v35
	v_pk_add_f32 v[36:37], v[36:37], v[196:197] op_sel:[0,1] op_sel_hi:[1,1] neg_lo:[0,1] neg_hi:[0,1]
	v_exp_f32_e32 v36, v36
	v_exp_f32_e32 v37, v37
	v_pk_add_f32 v[38:39], v[38:39], v[196:197] op_sel:[0,1] op_sel_hi:[1,1] neg_lo:[0,1] neg_hi:[0,1]
	v_exp_f32_e32 v38, v38
	v_exp_f32_e32 v39, v39
	v_pk_add_f32 v[40:41], v[40:41], v[196:197] op_sel:[0,1] op_sel_hi:[1,1] neg_lo:[0,1] neg_hi:[0,1]
	v_exp_f32_e32 v40, v40
	v_exp_f32_e32 v41, v41
	v_pk_add_f32 v[42:43], v[42:43], v[196:197] op_sel:[0,1] op_sel_hi:[1,1] neg_lo:[0,1] neg_hi:[0,1]
	v_add_f32_e32 v128, v143, v128
	v_exp_f32_e32 v42, v42
	v_add_f32_e32 v128, v144, v128
	v_exp_f32_e32 v43, v43
	v_pk_add_f32 v[44:45], v[44:45], v[196:197] op_sel:[0,1] op_sel_hi:[1,1] neg_lo:[0,1] neg_hi:[0,1]
	v_add_f32_e32 v128, v145, v128
	v_exp_f32_e32 v44, v44
	v_add_f32_e32 v128, v146, v128
	v_exp_f32_e32 v45, v45
	v_pk_add_f32 v[46:47], v[46:47], v[196:197] op_sel:[0,1] op_sel_hi:[1,1] neg_lo:[0,1] neg_hi:[0,1]
	v_add_f32_e32 v128, v147, v128
	v_exp_f32_e32 v46, v46
	v_add_f32_e32 v128, v148, v128
	v_exp_f32_e32 v47, v47
	v_cvt_pk_bf16_f32 v32, v129, v130
	v_cvt_pk_bf16_f32 v33, v131, v132
	v_cvt_pk_bf16_f32 v34, v36, v37
	v_cvt_pk_bf16_f32 v35, v38, v39
	v_add_f32_e32 v128, v149, v128
	v_add_f32_e32 v128, v150, v128
	v_mfma_f32_32x32x16_bf16 v[0:15], v[60:63], v[32:35], v[0:15]
	v_add_f32_e32 v128, v151, v128
	v_add_f32_e32 v128, v152, v128
	v_add_f32_e32 v128, v153, v128
	v_add_f32_e32 v128, v154, v128
	v_add_f32_e32 v128, v155, v128
	v_add_f32_e32 v128, v156, v128
	v_mfma_f32_32x32x16_bf16 v[16:31], v[56:59], v[32:35], v[16:31]
	v_cvt_pk_bf16_f32 v32, v40, v41
	v_cvt_pk_bf16_f32 v33, v42, v43
	v_cvt_pk_bf16_f32 v34, v44, v45
	v_cvt_pk_bf16_f32 v35, v46, v47
	s_nop 1
	v_mfma_f32_32x32x16_bf16 v[0:15], v[52:55], v[32:35], v[0:15]
	v_mfma_f32_32x32x16_bf16 v[16:31], v[48:51], v[32:35], v[16:31]
	v_add_f32_e32 v32, v129, v128
	v_add_f32_e32 v32, v130, v32
	v_add_f32_e32 v32, v131, v32
	v_add_f32_e32 v32, v132, v32
	v_add_f32_e32 v32, v36, v32
	v_add_f32_e32 v32, v37, v32
	v_add_f32_e32 v32, v38, v32
	v_add_f32_e32 v32, v39, v32
	v_add_f32_e32 v32, v40, v32
	v_add_f32_e32 v32, v41, v32
	v_add_f32_e32 v32, v42, v32
	v_add_f32_e32 v32, v43, v32
	v_add_f32_e32 v32, v44, v32
	v_add_f32_e32 v32, v45, v32
	v_add_f32_e32 v32, v46, v32
	v_add_f32_e32 v162, v47, v32
	v_cndmask_b32_e64 v32, 0, 1, s[0:1]
	v_cmp_ne_u32_e64 s[0:1], 1, v32
	s_cbranch_scc1 .LBB0_397
	ds_read_b128 v[32:35], v233 offset:9216
	ds_read_b128 v[128:131], v233 offset:9248
	ds_read_b128 v[132:135], v233 offset:9280
	ds_read_b128 v[136:139], v233 offset:9312
	ds_read_b128 v[36:39], v233 offset:13824
	ds_read_b128 v[140:143], v233 offset:13856
	ds_read_b128 v[144:147], v233 offset:13888
	ds_read_b128 v[148:151], v233 offset:13920
	s_waitcnt lgkmcnt(7)
	v_mfma_f32_32x32x16_bf16 v[48:63], v[32:35], v[108:111], 0
	s_and_b64 vcc, exec, s[0:1]
	s_waitcnt lgkmcnt(3)
	v_mfma_f32_32x32x16_bf16 v[32:47], v[36:39], v[108:111], 0
	v_mfma_f32_32x32x16_bf16 v[48:63], v[128:131], v[104:107], v[48:63]
	s_waitcnt lgkmcnt(2)
	v_mfma_f32_32x32x16_bf16 v[32:47], v[140:143], v[104:107], v[32:47]
	v_mfma_f32_32x32x16_bf16 v[48:63], v[132:135], v[100:103], v[48:63]
	s_waitcnt lgkmcnt(1)
	v_mfma_f32_32x32x16_bf16 v[32:47], v[144:147], v[100:103], v[32:47]
	v_mfma_f32_32x32x16_bf16 v[48:63], v[136:139], v[96:99], v[48:63]
	s_waitcnt lgkmcnt(0)
	v_mfma_f32_32x32x16_bf16 v[32:47], v[148:151], v[96:99], v[32:47]
	ds_read_b128 v[156:159], v234 offset:36992
	ds_read_b128 v[144:147], v234 offset:37024
	ds_read_b128 v[152:155], v234 offset:53888
	ds_read_b128 v[148:151], v234 offset:53920
	ds_read_b128 v[140:143], v234 offset:37056
	ds_read_b128 v[136:139], v234 offset:53952
	ds_read_b128 v[132:135], v234 offset:37088
	ds_read_b128 v[128:131], v234 offset:53984
	s_cbranch_vccnz .LBB0_395
	v_add_u32_e32 v244, s88, v240
	v_subrev_u32_e32 v245, 64, v244
	v_cmp_gt_i32_e32 vcc, v203, v245
	v_add_u32_e32 v244, 0xffffffa0, v244
	s_nop 0
	v_cndmask_b32_e32 v246, v48, v235, vcc
	v_cmp_lt_i32_e32 vcc, v203, v245
	s_nop 1
	v_cndmask_b32_e32 v48, v246, v48, vcc
	v_cndmask_b32_e32 v49, v235, v49, vcc
	v_cmp_le_i32_e32 vcc, v204, v245
	s_nop 1
	v_cndmask_b32_e32 v50, v235, v50, vcc
	v_cmp_le_i32_e32 vcc, v205, v245
	s_nop 1
	v_cndmask_b32_e32 v51, v235, v51, vcc
	v_cmp_le_i32_e32 vcc, v206, v245
	s_nop 1
	v_cndmask_b32_e32 v52, v235, v52, vcc
	v_cmp_le_i32_e32 vcc, v207, v245
	s_nop 1
	v_cndmask_b32_e32 v53, v235, v53, vcc
	v_cmp_le_i32_e32 vcc, v208, v245
	s_nop 1
	v_cndmask_b32_e32 v54, v235, v54, vcc
	v_cmp_le_i32_e32 vcc, v209, v245
	s_nop 1
	v_cndmask_b32_e32 v55, v235, v55, vcc
	v_cmp_le_i32_e32 vcc, v210, v245
	s_nop 1
	v_cndmask_b32_e32 v56, v235, v56, vcc
	v_cmp_le_i32_e32 vcc, v211, v245
	s_nop 1
	v_cndmask_b32_e32 v57, v235, v57, vcc
	v_cmp_le_i32_e32 vcc, v212, v245
	s_nop 1
	v_cndmask_b32_e32 v58, v235, v58, vcc
	v_cmp_le_i32_e32 vcc, v213, v245
	s_nop 1
	v_cndmask_b32_e32 v59, v235, v59, vcc
	v_cmp_le_i32_e32 vcc, v214, v245
	s_nop 1
	v_cndmask_b32_e32 v60, v235, v60, vcc
	v_cmp_le_i32_e32 vcc, v216, v245
	s_nop 1
	v_cndmask_b32_e32 v61, v235, v61, vcc
	v_cmp_le_i32_e32 vcc, v217, v245
	s_nop 1
	v_cndmask_b32_e32 v62, v235, v62, vcc
	v_cmp_le_i32_e32 vcc, v218, v245
	s_nop 1
	v_cndmask_b32_e32 v63, v235, v63, vcc
	v_cmp_le_i32_e32 vcc, v203, v244
	s_nop 1
	v_cndmask_b32_e32 v32, v235, v32, vcc
	v_cmp_lt_i32_e32 vcc, v203, v244
	s_nop 1
	v_cndmask_b32_e32 v33, v235, v33, vcc
	v_cmp_le_i32_e32 vcc, v204, v244
	s_nop 1
	v_cndmask_b32_e32 v34, v235, v34, vcc
	v_cmp_le_i32_e32 vcc, v205, v244
	s_nop 1
	v_cndmask_b32_e32 v35, v235, v35, vcc
	v_cmp_le_i32_e32 vcc, v206, v244
	s_nop 1
	v_cndmask_b32_e32 v36, v235, v36, vcc
	v_cmp_le_i32_e32 vcc, v207, v244
	s_nop 1
	v_cndmask_b32_e32 v37, v235, v37, vcc
	v_cmp_le_i32_e32 vcc, v208, v244
	s_nop 1
	v_cndmask_b32_e32 v38, v235, v38, vcc
	v_cmp_le_i32_e32 vcc, v209, v244
	s_nop 1
	v_cndmask_b32_e32 v39, v235, v39, vcc
	v_cmp_le_i32_e32 vcc, v210, v244
	s_nop 1
	v_cndmask_b32_e32 v40, v235, v40, vcc
	v_cmp_le_i32_e32 vcc, v211, v244
	s_nop 1
	v_cndmask_b32_e32 v41, v235, v41, vcc
	v_cmp_le_i32_e32 vcc, v212, v244
	s_nop 1
	v_cndmask_b32_e32 v42, v235, v42, vcc
	v_cmp_le_i32_e32 vcc, v213, v244
	s_nop 1
	v_cndmask_b32_e32 v43, v235, v43, vcc
	v_cmp_le_i32_e32 vcc, v214, v244
	s_nop 1
	v_cndmask_b32_e32 v44, v235, v44, vcc
	v_cmp_le_i32_e32 vcc, v216, v244
	s_nop 1
	v_cndmask_b32_e32 v45, v235, v45, vcc
	v_cmp_le_i32_e32 vcc, v217, v244
	s_nop 1
	v_cndmask_b32_e32 v46, v235, v46, vcc
	v_cmp_le_i32_e32 vcc, v218, v244
	s_nop 1
	v_cndmask_b32_e32 v47, v235, v47, vcc
.LBB0_395:
	s_nop 0
	v_max3_f32 v244, v48, s38, v49
	v_max3_f32 v244, v244, v50, v51
	v_max3_f32 v244, v244, v52, v53
	v_max3_f32 v244, v244, v54, v55
	v_max3_f32 v244, v244, v56, v57
	v_max3_f32 v244, v244, v58, v59
	v_max3_f32 v244, v244, v60, v61
	v_max3_f32 v244, v244, v62, v63
	v_max3_f32 v244, v244, v32, v33
	v_max3_f32 v244, v244, v34, v35
	v_max3_f32 v244, v244, v36, v37
	v_max3_f32 v244, v244, v38, v39
	v_max3_f32 v244, v244, v40, v41
	v_max3_f32 v244, v244, v42, v43
	v_max3_f32 v244, v244, v44, v45
	v_max3_f32 v244, v244, v46, v47
	ds_bpermute_b32 v245, v238, v244
	s_waitcnt lgkmcnt(0)
	v_max3_f32 v245, v197, v244, v245
	v_sub_f32_e32 v197, v197, v245
	v_pk_add_f32 v[48:49], v[48:49], v[244:245] op_sel:[0,1] op_sel_hi:[1,1] neg_lo:[0,1] neg_hi:[0,1]
	v_exp_f32_e32 v244, v197
	v_exp_f32_e32 v197, v48
	v_exp_f32_e32 v246, v49
	v_pk_add_f32 v[50:51], v[50:51], v[244:245] op_sel:[0,1] op_sel_hi:[1,1] neg_lo:[0,1] neg_hi:[0,1]
	v_exp_f32_e32 v247, v50
	v_exp_f32_e32 v248, v51
	v_pk_add_f32 v[52:53], v[52:53], v[244:245] op_sel:[0,1] op_sel_hi:[1,1] neg_lo:[0,1] neg_hi:[0,1]
	v_exp_f32_e32 v52, v52
	v_exp_f32_e32 v53, v53
	v_pk_add_f32 v[54:55], v[54:55], v[244:245] op_sel:[0,1] op_sel_hi:[1,1] neg_lo:[0,1] neg_hi:[0,1]
	v_exp_f32_e32 v54, v54
	v_exp_f32_e32 v55, v55
	v_pk_add_f32 v[56:57], v[56:57], v[244:245] op_sel:[0,1] op_sel_hi:[1,1] neg_lo:[0,1] neg_hi:[0,1]
	v_exp_f32_e32 v56, v56
	v_exp_f32_e32 v57, v57
	v_pk_add_f32 v[58:59], v[58:59], v[244:245] op_sel:[0,1] op_sel_hi:[1,1] neg_lo:[0,1] neg_hi:[0,1]
	v_exp_f32_e32 v58, v58
	v_exp_f32_e32 v59, v59
	v_pk_add_f32 v[60:61], v[60:61], v[244:245] op_sel:[0,1] op_sel_hi:[1,1] neg_lo:[0,1] neg_hi:[0,1]
	v_exp_f32_e32 v60, v60
	v_exp_f32_e32 v61, v61
	v_pk_add_f32 v[62:63], v[62:63], v[244:245] op_sel:[0,1] op_sel_hi:[1,1] neg_lo:[0,1] neg_hi:[0,1]
	v_exp_f32_e32 v62, v62
	v_exp_f32_e32 v63, v63
	v_cvt_pk_bf16_f32 v48, v197, v246
	v_cvt_pk_bf16_f32 v49, v247, v248
	v_cvt_pk_bf16_f32 v50, v52, v53
	v_cvt_pk_bf16_f32 v51, v54, v55
	v_pk_mul_f32 v[14:15], v[14:15], v[244:245] op_sel_hi:[1,0]
	v_pk_mul_f32 v[12:13], v[12:13], v[244:245] op_sel_hi:[1,0]
	v_pk_mul_f32 v[10:11], v[10:11], v[244:245] op_sel_hi:[1,0]
	v_pk_mul_f32 v[8:9], v[8:9], v[244:245] op_sel_hi:[1,0]
	v_pk_mul_f32 v[6:7], v[6:7], v[244:245] op_sel_hi:[1,0]
	v_pk_mul_f32 v[4:5], v[4:5], v[244:245] op_sel_hi:[1,0]
	v_pk_mul_f32 v[2:3], v[2:3], v[244:245] op_sel_hi:[1,0]
	v_pk_mul_f32 v[0:1], v[0:1], v[244:245] op_sel_hi:[1,0]
	v_pk_mul_f32 v[30:31], v[30:31], v[244:245] op_sel_hi:[1,0]
	v_pk_mul_f32 v[28:29], v[28:29], v[244:245] op_sel_hi:[1,0]
	v_pk_mul_f32 v[26:27], v[26:27], v[244:245] op_sel_hi:[1,0]
	v_pk_mul_f32 v[24:25], v[24:25], v[244:245] op_sel_hi:[1,0]
	v_pk_mul_f32 v[22:23], v[22:23], v[244:245] op_sel_hi:[1,0]
	v_pk_mul_f32 v[20:21], v[20:21], v[244:245] op_sel_hi:[1,0]
	v_pk_mul_f32 v[18:19], v[18:19], v[244:245] op_sel_hi:[1,0]
	v_pk_mul_f32 v[16:17], v[16:17], v[244:245] op_sel_hi:[1,0]
	v_mfma_f32_32x32x16_bf16 v[0:15], v[156:159], v[48:51], v[0:15]
	v_fmac_f32_e32 v197, v162, v244
	v_pk_add_f32 v[32:33], v[32:33], v[244:245] op_sel:[0,1] op_sel_hi:[1,1] neg_lo:[0,1] neg_hi:[0,1]
	v_mfma_f32_32x32x16_bf16 v[16:31], v[152:155], v[48:51], v[16:31]
	v_cvt_pk_bf16_f32 v48, v56, v57
	v_cvt_pk_bf16_f32 v49, v58, v59
	v_cvt_pk_bf16_f32 v50, v60, v61
	v_cvt_pk_bf16_f32 v51, v62, v63
	s_nop 1
	v_mfma_f32_32x32x16_bf16 v[0:15], v[144:147], v[48:51], v[0:15]
	v_mfma_f32_32x32x16_bf16 v[16:31], v[148:151], v[48:51], v[16:31]
	v_add_f32_e32 v48, v246, v197
	v_exp_f32_e32 v49, v32
	v_add_f32_e32 v48, v247, v48
	v_exp_f32_e32 v50, v33
	v_pk_add_f32 v[34:35], v[34:35], v[244:245] op_sel:[0,1] op_sel_hi:[1,1] neg_lo:[0,1] neg_hi:[0,1]
	v_add_f32_e32 v48, v248, v48
	v_exp_f32_e32 v51, v34
	v_add_f32_e32 v48, v52, v48
	v_exp_f32_e32 v52, v35
	v_pk_add_f32 v[36:37], v[36:37], v[244:245] op_sel:[0,1] op_sel_hi:[1,1] neg_lo:[0,1] neg_hi:[0,1]
	v_exp_f32_e32 v36, v36
	v_exp_f32_e32 v37, v37
	v_pk_add_f32 v[38:39], v[38:39], v[244:245] op_sel:[0,1] op_sel_hi:[1,1] neg_lo:[0,1] neg_hi:[0,1]
	v_exp_f32_e32 v38, v38
	v_exp_f32_e32 v39, v39
	v_pk_add_f32 v[40:41], v[40:41], v[244:245] op_sel:[0,1] op_sel_hi:[1,1] neg_lo:[0,1] neg_hi:[0,1]
	v_exp_f32_e32 v40, v40
	v_exp_f32_e32 v41, v41
	v_pk_add_f32 v[42:43], v[42:43], v[244:245] op_sel:[0,1] op_sel_hi:[1,1] neg_lo:[0,1] neg_hi:[0,1]
	v_exp_f32_e32 v42, v42
	v_exp_f32_e32 v43, v43
	v_pk_add_f32 v[44:45], v[44:45], v[244:245] op_sel:[0,1] op_sel_hi:[1,1] neg_lo:[0,1] neg_hi:[0,1]
	v_exp_f32_e32 v44, v44
	v_add_f32_e32 v48, v53, v48
	v_exp_f32_e32 v45, v45
	v_pk_add_f32 v[46:47], v[46:47], v[244:245] op_sel:[0,1] op_sel_hi:[1,1] neg_lo:[0,1] neg_hi:[0,1]
	v_add_f32_e32 v48, v54, v48
	v_exp_f32_e32 v46, v46
	v_add_f32_e32 v48, v55, v48
	v_exp_f32_e32 v47, v47
	v_cvt_pk_bf16_f32 v32, v49, v50
	v_cvt_pk_bf16_f32 v33, v51, v52
	v_cvt_pk_bf16_f32 v34, v36, v37
	v_cvt_pk_bf16_f32 v35, v38, v39
	v_add_f32_e32 v48, v56, v48
	v_add_f32_e32 v48, v57, v48
	v_mfma_f32_32x32x16_bf16 v[0:15], v[140:143], v[32:35], v[0:15]
	v_add_f32_e32 v48, v58, v48
	v_add_f32_e32 v48, v59, v48
	v_add_f32_e32 v48, v60, v48
	v_add_f32_e32 v48, v61, v48
	v_add_f32_e32 v48, v62, v48
	v_add_f32_e32 v48, v63, v48
	v_mov_b32_e32 v197, v245
	v_mfma_f32_32x32x16_bf16 v[16:31], v[136:139], v[32:35], v[16:31]
	v_cvt_pk_bf16_f32 v32, v40, v41
	v_cvt_pk_bf16_f32 v33, v42, v43
	v_cvt_pk_bf16_f32 v34, v44, v45
	v_cvt_pk_bf16_f32 v35, v46, v47
	s_nop 1
	v_mfma_f32_32x32x16_bf16 v[0:15], v[132:135], v[32:35], v[0:15]
	v_mfma_f32_32x32x16_bf16 v[16:31], v[128:131], v[32:35], v[16:31]
	v_add_f32_e32 v32, v49, v48
	v_add_f32_e32 v32, v50, v32
	v_add_f32_e32 v32, v51, v32
	v_add_f32_e32 v32, v52, v32
	v_add_f32_e32 v32, v36, v32
	v_add_f32_e32 v32, v37, v32
	v_add_f32_e32 v32, v38, v32
	v_add_f32_e32 v32, v39, v32
	v_add_f32_e32 v32, v40, v32
	v_add_f32_e32 v32, v41, v32
	v_add_f32_e32 v32, v42, v32
	v_add_f32_e32 v32, v43, v32
	v_add_f32_e32 v32, v44, v32
	v_add_f32_e32 v32, v45, v32
	v_add_f32_e32 v32, v46, v32
	v_add_f32_e32 v162, v47, v32
	s_cmp_lt_u32 s58, 4
	s_cbranch_scc0 .LBB0_398

.LBB0_400:
	s_nop 0
	v_max3_f32 v244, v48, s38, v49
	v_max3_f32 v244, v244, v50, v51
	v_max3_f32 v244, v244, v52, v53
	v_max3_f32 v244, v244, v54, v55
	v_max3_f32 v244, v244, v56, v57
	v_max3_f32 v244, v244, v58, v59
	v_max3_f32 v244, v244, v60, v61
	v_max3_f32 v244, v244, v62, v63
	v_max3_f32 v244, v244, v32, v33
	v_max3_f32 v244, v244, v34, v35
	v_max3_f32 v244, v244, v36, v37
	v_max3_f32 v244, v244, v38, v39
	v_max3_f32 v244, v244, v40, v41
	v_max3_f32 v244, v244, v42, v43
	v_max3_f32 v244, v244, v44, v45
	v_max3_f32 v244, v244, v46, v47
	ds_bpermute_b32 v245, v238, v244
	s_waitcnt lgkmcnt(0)
	v_max3_f32 v245, v197, v244, v245
	v_sub_f32_e32 v197, v197, v245
	v_pk_add_f32 v[48:49], v[48:49], v[244:245] op_sel:[0,1] op_sel_hi:[1,1] neg_lo:[0,1] neg_hi:[0,1]
	v_exp_f32_e32 v244, v197
	v_exp_f32_e32 v197, v48
	v_exp_f32_e32 v246, v49
	v_pk_add_f32 v[50:51], v[50:51], v[244:245] op_sel:[0,1] op_sel_hi:[1,1] neg_lo:[0,1] neg_hi:[0,1]
	v_exp_f32_e32 v247, v50
	v_exp_f32_e32 v248, v51
	v_pk_add_f32 v[52:53], v[52:53], v[244:245] op_sel:[0,1] op_sel_hi:[1,1] neg_lo:[0,1] neg_hi:[0,1]
	v_exp_f32_e32 v52, v52
	v_exp_f32_e32 v53, v53
	v_pk_add_f32 v[54:55], v[54:55], v[244:245] op_sel:[0,1] op_sel_hi:[1,1] neg_lo:[0,1] neg_hi:[0,1]
	v_exp_f32_e32 v54, v54
	v_exp_f32_e32 v55, v55
	v_pk_add_f32 v[56:57], v[56:57], v[244:245] op_sel:[0,1] op_sel_hi:[1,1] neg_lo:[0,1] neg_hi:[0,1]
	v_exp_f32_e32 v56, v56
	v_exp_f32_e32 v57, v57
	v_pk_add_f32 v[58:59], v[58:59], v[244:245] op_sel:[0,1] op_sel_hi:[1,1] neg_lo:[0,1] neg_hi:[0,1]
	v_exp_f32_e32 v58, v58
	v_exp_f32_e32 v59, v59
	v_pk_add_f32 v[60:61], v[60:61], v[244:245] op_sel:[0,1] op_sel_hi:[1,1] neg_lo:[0,1] neg_hi:[0,1]
	v_exp_f32_e32 v60, v60
	v_exp_f32_e32 v61, v61
	v_pk_add_f32 v[62:63], v[62:63], v[244:245] op_sel:[0,1] op_sel_hi:[1,1] neg_lo:[0,1] neg_hi:[0,1]
	v_exp_f32_e32 v62, v62
	v_pk_mul_f32 v[0:1], v[0:1], v[244:245] op_sel_hi:[1,0]
	v_pk_mul_f32 v[16:17], v[16:17], v[244:245] op_sel_hi:[1,0]
	v_pk_mul_f32 v[2:3], v[2:3], v[244:245] op_sel_hi:[1,0]
	v_pk_mul_f32 v[18:19], v[18:19], v[244:245] op_sel_hi:[1,0]
	v_pk_mul_f32 v[4:5], v[4:5], v[244:245] op_sel_hi:[1,0]
	v_pk_mul_f32 v[20:21], v[20:21], v[244:245] op_sel_hi:[1,0]
	v_pk_mul_f32 v[6:7], v[6:7], v[244:245] op_sel_hi:[1,0]
	v_pk_mul_f32 v[22:23], v[22:23], v[244:245] op_sel_hi:[1,0]
	v_pk_mul_f32 v[8:9], v[8:9], v[244:245] op_sel_hi:[1,0]
	v_pk_mul_f32 v[24:25], v[24:25], v[244:245] op_sel_hi:[1,0]
	v_pk_mul_f32 v[10:11], v[10:11], v[244:245] op_sel_hi:[1,0]
	v_pk_mul_f32 v[26:27], v[26:27], v[244:245] op_sel_hi:[1,0]
	v_pk_mul_f32 v[12:13], v[12:13], v[244:245] op_sel_hi:[1,0]
	v_pk_mul_f32 v[28:29], v[28:29], v[244:245] op_sel_hi:[1,0]
	v_pk_mul_f32 v[14:15], v[14:15], v[244:245] op_sel_hi:[1,0]
	v_pk_mul_f32 v[30:31], v[30:31], v[244:245] op_sel_hi:[1,0]
	v_exp_f32_e32 v63, v63
	v_cvt_pk_bf16_f32 v48, v197, v246
	v_cvt_pk_bf16_f32 v49, v247, v248
	v_cvt_pk_bf16_f32 v50, v52, v53
	v_cvt_pk_bf16_f32 v51, v54, v55
	v_fmac_f32_e32 v197, v162, v244
	v_pk_add_f32 v[32:33], v[32:33], v[244:245] op_sel:[0,1] op_sel_hi:[1,1] neg_lo:[0,1] neg_hi:[0,1]
	v_mfma_f32_32x32x16_bf16 v[0:15], v[156:159], v[48:51], v[0:15]
	v_mfma_f32_32x32x16_bf16 v[16:31], v[152:155], v[48:51], v[16:31]
	v_cvt_pk_bf16_f32 v48, v56, v57
	v_cvt_pk_bf16_f32 v49, v58, v59
	v_cvt_pk_bf16_f32 v50, v60, v61
	v_cvt_pk_bf16_f32 v51, v62, v63
	s_nop 1
	v_mfma_f32_32x32x16_bf16 v[0:15], v[144:147], v[48:51], v[0:15]
	v_mfma_f32_32x32x16_bf16 v[16:31], v[148:151], v[48:51], v[16:31]
	v_add_f32_e32 v48, v246, v197
	v_exp_f32_e32 v49, v32
	v_add_f32_e32 v48, v247, v48
	v_exp_f32_e32 v50, v33
	v_pk_add_f32 v[34:35], v[34:35], v[244:245] op_sel:[0,1] op_sel_hi:[1,1] neg_lo:[0,1] neg_hi:[0,1]
	v_add_f32_e32 v48, v248, v48
	v_exp_f32_e32 v51, v34
	v_add_f32_e32 v48, v52, v48
	v_exp_f32_e32 v52, v35
	v_pk_add_f32 v[36:37], v[36:37], v[244:245] op_sel:[0,1] op_sel_hi:[1,1] neg_lo:[0,1] neg_hi:[0,1]
	v_exp_f32_e32 v36, v36
	v_exp_f32_e32 v37, v37
	v_pk_add_f32 v[38:39], v[38:39], v[244:245] op_sel:[0,1] op_sel_hi:[1,1] neg_lo:[0,1] neg_hi:[0,1]
	v_exp_f32_e32 v38, v38
	v_exp_f32_e32 v39, v39
	v_pk_add_f32 v[40:41], v[40:41], v[244:245] op_sel:[0,1] op_sel_hi:[1,1] neg_lo:[0,1] neg_hi:[0,1]
	v_exp_f32_e32 v40, v40
	v_exp_f32_e32 v41, v41
	v_pk_add_f32 v[42:43], v[42:43], v[244:245] op_sel:[0,1] op_sel_hi:[1,1] neg_lo:[0,1] neg_hi:[0,1]
	v_exp_f32_e32 v42, v42
	v_exp_f32_e32 v43, v43
	v_pk_add_f32 v[44:45], v[44:45], v[244:245] op_sel:[0,1] op_sel_hi:[1,1] neg_lo:[0,1] neg_hi:[0,1]
	v_exp_f32_e32 v44, v44
	v_add_f32_e32 v48, v53, v48
	v_exp_f32_e32 v45, v45
	v_pk_add_f32 v[46:47], v[46:47], v[244:245] op_sel:[0,1] op_sel_hi:[1,1] neg_lo:[0,1] neg_hi:[0,1]
	v_add_f32_e32 v48, v54, v48
	v_exp_f32_e32 v46, v46
	v_add_f32_e32 v48, v55, v48
	v_exp_f32_e32 v47, v47
	v_cvt_pk_bf16_f32 v32, v49, v50
	v_cvt_pk_bf16_f32 v33, v51, v52
	v_cvt_pk_bf16_f32 v34, v36, v37
	v_cvt_pk_bf16_f32 v35, v38, v39
	v_add_f32_e32 v48, v56, v48
	v_add_f32_e32 v48, v57, v48
	v_mfma_f32_32x32x16_bf16 v[0:15], v[140:143], v[32:35], v[0:15]
	v_add_f32_e32 v48, v58, v48
	v_add_f32_e32 v48, v59, v48
	v_add_f32_e32 v48, v60, v48
	v_add_f32_e32 v48, v61, v48
	v_add_f32_e32 v48, v62, v48
	v_add_f32_e32 v48, v63, v48
	v_mov_b32_e32 v197, v245
	v_mfma_f32_32x32x16_bf16 v[16:31], v[136:139], v[32:35], v[16:31]
	v_cvt_pk_bf16_f32 v32, v40, v41
	v_cvt_pk_bf16_f32 v33, v42, v43
	v_cvt_pk_bf16_f32 v34, v44, v45
	v_cvt_pk_bf16_f32 v35, v46, v47
	s_nop 1
	v_mfma_f32_32x32x16_bf16 v[0:15], v[132:135], v[32:35], v[0:15]
	v_mfma_f32_32x32x16_bf16 v[16:31], v[128:131], v[32:35], v[16:31]
	v_add_f32_e32 v32, v49, v48
	v_add_f32_e32 v32, v50, v32
	v_add_f32_e32 v32, v51, v32
	v_add_f32_e32 v32, v52, v32
	v_add_f32_e32 v32, v36, v32
	v_add_f32_e32 v32, v37, v32
	v_add_f32_e32 v32, v38, v32
	v_add_f32_e32 v32, v39, v32
	v_add_f32_e32 v32, v40, v32
	v_add_f32_e32 v32, v41, v32
	v_add_f32_e32 v32, v42, v32
	v_add_f32_e32 v32, v43, v32
	v_add_f32_e32 v32, v44, v32
	v_add_f32_e32 v32, v45, v32
	v_add_f32_e32 v32, v46, v32
	v_add_f32_e32 v162, v47, v32
	s_cmp_lt_u32 s58, 6
	s_cbranch_scc1 .LBB0_404

.LBB0_403:
	s_nop 0
	v_max3_f32 v96, v48, s38, v49
	v_max3_f32 v96, v96, v50, v51
	v_max3_f32 v96, v96, v52, v53
	v_max3_f32 v96, v96, v54, v55
	v_max3_f32 v96, v96, v56, v57
	v_max3_f32 v96, v96, v58, v59
	v_max3_f32 v96, v96, v60, v61
	v_max3_f32 v96, v96, v62, v63
	s_nop 1
	v_max3_f32 v96, v96, v32, v33
	v_max3_f32 v96, v96, v34, v35
	v_max3_f32 v96, v96, v36, v37
	v_max3_f32 v96, v96, v38, v39
	v_max3_f32 v96, v96, v40, v41
	v_max3_f32 v96, v96, v42, v43
	v_max3_f32 v96, v96, v44, v45
	v_max3_f32 v96, v96, v46, v47
	ds_bpermute_b32 v97, v238, v96
	s_waitcnt lgkmcnt(0)
	v_max3_f32 v97, v197, v96, v97
	v_pk_add_f32 v[48:49], v[48:49], v[96:97] op_sel:[0,1] op_sel_hi:[1,1] neg_lo:[0,1] neg_hi:[0,1]
	v_exp_f32_e32 v98, v48
	v_exp_f32_e32 v99, v49
	v_pk_add_f32 v[50:51], v[50:51], v[96:97] op_sel:[0,1] op_sel_hi:[1,1] neg_lo:[0,1] neg_hi:[0,1]
	v_exp_f32_e32 v148, v50
	v_exp_f32_e32 v149, v51
	v_pk_add_f32 v[52:53], v[52:53], v[96:97] op_sel:[0,1] op_sel_hi:[1,1] neg_lo:[0,1] neg_hi:[0,1]
	v_exp_f32_e32 v52, v52
	v_exp_f32_e32 v53, v53
	v_pk_add_f32 v[54:55], v[54:55], v[96:97] op_sel:[0,1] op_sel_hi:[1,1] neg_lo:[0,1] neg_hi:[0,1]
	v_exp_f32_e32 v54, v54
	v_exp_f32_e32 v55, v55
	v_pk_add_f32 v[56:57], v[56:57], v[96:97] op_sel:[0,1] op_sel_hi:[1,1] neg_lo:[0,1] neg_hi:[0,1]
	v_exp_f32_e32 v56, v56
	v_exp_f32_e32 v57, v57
	v_pk_add_f32 v[58:59], v[58:59], v[96:97] op_sel:[0,1] op_sel_hi:[1,1] neg_lo:[0,1] neg_hi:[0,1]
	v_sub_f32_e32 v96, v197, v97
	v_exp_f32_e32 v58, v58
	v_exp_f32_e32 v96, v96
	v_exp_f32_e32 v59, v59
	v_pk_add_f32 v[60:61], v[60:61], v[96:97] op_sel:[0,1] op_sel_hi:[1,1] neg_lo:[0,1] neg_hi:[0,1]
	v_exp_f32_e32 v60, v60
	v_exp_f32_e32 v61, v61
	v_pk_add_f32 v[62:63], v[62:63], v[96:97] op_sel:[0,1] op_sel_hi:[1,1] neg_lo:[0,1] neg_hi:[0,1]
	v_exp_f32_e32 v62, v62
	v_pk_mul_f32 v[0:1], v[0:1], v[96:97] op_sel_hi:[1,0]
	v_pk_mul_f32 v[16:17], v[16:17], v[96:97] op_sel_hi:[1,0]
	v_pk_mul_f32 v[2:3], v[2:3], v[96:97] op_sel_hi:[1,0]
	v_pk_mul_f32 v[18:19], v[18:19], v[96:97] op_sel_hi:[1,0]
	v_pk_mul_f32 v[4:5], v[4:5], v[96:97] op_sel_hi:[1,0]
	v_pk_mul_f32 v[20:21], v[20:21], v[96:97] op_sel_hi:[1,0]
	v_pk_mul_f32 v[6:7], v[6:7], v[96:97] op_sel_hi:[1,0]
	v_pk_mul_f32 v[22:23], v[22:23], v[96:97] op_sel_hi:[1,0]
	v_pk_mul_f32 v[8:9], v[8:9], v[96:97] op_sel_hi:[1,0]
	v_pk_mul_f32 v[24:25], v[24:25], v[96:97] op_sel_hi:[1,0]
	v_pk_mul_f32 v[10:11], v[10:11], v[96:97] op_sel_hi:[1,0]
	v_pk_mul_f32 v[26:27], v[26:27], v[96:97] op_sel_hi:[1,0]
	v_pk_mul_f32 v[12:13], v[12:13], v[96:97] op_sel_hi:[1,0]
	v_pk_mul_f32 v[28:29], v[28:29], v[96:97] op_sel_hi:[1,0]
	v_pk_mul_f32 v[14:15], v[14:15], v[96:97] op_sel_hi:[1,0]
	v_pk_mul_f32 v[30:31], v[30:31], v[96:97] op_sel_hi:[1,0]
	v_exp_f32_e32 v63, v63
	v_cvt_pk_bf16_f32 v48, v98, v99
	v_cvt_pk_bf16_f32 v49, v148, v149
	v_cvt_pk_bf16_f32 v50, v52, v53
	v_cvt_pk_bf16_f32 v51, v54, v55
	v_fmac_f32_e32 v98, v162, v96
	v_pk_add_f32 v[32:33], v[32:33], v[96:97] op_sel:[0,1] op_sel_hi:[1,1] neg_lo:[0,1] neg_hi:[0,1]
	v_mfma_f32_32x32x16_bf16 v[0:15], v[144:147], v[48:51], v[0:15]
	v_mov_b32_e32 v197, v97
	v_mfma_f32_32x32x16_bf16 v[16:31], v[140:143], v[48:51], v[16:31]
	v_cvt_pk_bf16_f32 v48, v56, v57
	v_cvt_pk_bf16_f32 v49, v58, v59
	v_cvt_pk_bf16_f32 v50, v60, v61
	v_cvt_pk_bf16_f32 v51, v62, v63
	s_nop 1
	v_mfma_f32_32x32x16_bf16 v[0:15], v[132:135], v[48:51], v[0:15]
	v_mfma_f32_32x32x16_bf16 v[16:31], v[136:139], v[48:51], v[16:31]
	v_add_f32_e32 v48, v99, v98
	v_exp_f32_e32 v49, v32
	v_add_f32_e32 v48, v148, v48
	v_exp_f32_e32 v50, v33
	v_pk_add_f32 v[34:35], v[34:35], v[96:97] op_sel:[0,1] op_sel_hi:[1,1] neg_lo:[0,1] neg_hi:[0,1]
	v_add_f32_e32 v48, v149, v48
	v_exp_f32_e32 v51, v34
	v_add_f32_e32 v48, v52, v48
	v_exp_f32_e32 v52, v35
	v_pk_add_f32 v[36:37], v[36:37], v[96:97] op_sel:[0,1] op_sel_hi:[1,1] neg_lo:[0,1] neg_hi:[0,1]
	v_exp_f32_e32 v36, v36
	v_exp_f32_e32 v37, v37
	v_pk_add_f32 v[38:39], v[38:39], v[96:97] op_sel:[0,1] op_sel_hi:[1,1] neg_lo:[0,1] neg_hi:[0,1]
	v_exp_f32_e32 v38, v38
	v_exp_f32_e32 v39, v39
	v_pk_add_f32 v[40:41], v[40:41], v[96:97] op_sel:[0,1] op_sel_hi:[1,1] neg_lo:[0,1] neg_hi:[0,1]
	v_exp_f32_e32 v40, v40
	v_exp_f32_e32 v41, v41
	v_pk_add_f32 v[42:43], v[42:43], v[96:97] op_sel:[0,1] op_sel_hi:[1,1] neg_lo:[0,1] neg_hi:[0,1]
	v_exp_f32_e32 v42, v42
	v_exp_f32_e32 v43, v43
	v_pk_add_f32 v[44:45], v[44:45], v[96:97] op_sel:[0,1] op_sel_hi:[1,1] neg_lo:[0,1] neg_hi:[0,1]
	v_exp_f32_e32 v44, v44
	v_add_f32_e32 v48, v53, v48
	v_exp_f32_e32 v45, v45
	v_pk_add_f32 v[46:47], v[46:47], v[96:97] op_sel:[0,1] op_sel_hi:[1,1] neg_lo:[0,1] neg_hi:[0,1]
	v_add_f32_e32 v48, v54, v48
	v_exp_f32_e32 v46, v46
	v_add_f32_e32 v48, v55, v48
	v_exp_f32_e32 v47, v47
	v_cvt_pk_bf16_f32 v32, v49, v50
	v_cvt_pk_bf16_f32 v33, v51, v52
	v_cvt_pk_bf16_f32 v34, v36, v37
	v_cvt_pk_bf16_f32 v35, v38, v39
	v_add_f32_e32 v48, v56, v48
	v_add_f32_e32 v48, v57, v48
	v_mfma_f32_32x32x16_bf16 v[0:15], v[128:131], v[32:35], v[0:15]
	v_add_f32_e32 v48, v58, v48
	v_add_f32_e32 v48, v59, v48
	v_add_f32_e32 v48, v60, v48
	v_add_f32_e32 v48, v61, v48
	v_add_f32_e32 v48, v62, v48
	v_add_f32_e32 v48, v63, v48
	v_mfma_f32_32x32x16_bf16 v[16:31], v[108:111], v[32:35], v[16:31]
	v_cvt_pk_bf16_f32 v32, v40, v41
	v_cvt_pk_bf16_f32 v33, v42, v43
	v_cvt_pk_bf16_f32 v34, v44, v45
	v_cvt_pk_bf16_f32 v35, v46, v47
	s_nop 1
	v_mfma_f32_32x32x16_bf16 v[0:15], v[104:107], v[32:35], v[0:15]
	v_mfma_f32_32x32x16_bf16 v[16:31], v[100:103], v[32:35], v[16:31]
	v_add_f32_e32 v32, v49, v48
	v_add_f32_e32 v32, v50, v32
	v_add_f32_e32 v32, v51, v32
	v_add_f32_e32 v32, v52, v32
	v_add_f32_e32 v32, v36, v32
	v_add_f32_e32 v32, v37, v32
	v_add_f32_e32 v32, v38, v32
	v_add_f32_e32 v32, v39, v32
	v_add_f32_e32 v32, v40, v32
	v_add_f32_e32 v32, v41, v32
	v_add_f32_e32 v32, v42, v32
	v_add_f32_e32 v32, v43, v32
	v_add_f32_e32 v32, v44, v32
	v_add_f32_e32 v32, v45, v32
	v_add_f32_e32 v32, v46, v32
	v_add_f32_e32 v162, v47, v32

.LBB0_846:
	s_nop 0
	v_max3_f32 v99, v48, s84, v49
	v_max3_f32 v99, v99, v50, v51
	v_max3_f32 v99, v99, v52, v53
	v_max3_f32 v99, v99, v54, v55
	v_max3_f32 v99, v99, v56, v57
	v_max3_f32 v99, v99, v58, v59
	v_max3_f32 v99, v99, v60, v61
	v_max3_f32 v99, v99, v62, v63
	v_max3_f32 v99, v99, v32, v33
	v_max3_f32 v99, v99, v34, v35
	v_max3_f32 v99, v99, v36, v37
	v_max3_f32 v99, v99, v38, v39
	v_max3_f32 v99, v99, v40, v41
	v_max3_f32 v99, v99, v42, v43
	v_max3_f32 v99, v99, v44, v45
	v_max3_f32 v245, v99, v46, v47
	v_and_b32_e32 v99, 64, v242
	v_xor_b32_e32 v243, 32, v242
	v_add_u32_e32 v244, 64, v99
	v_cmp_lt_i32_e32 vcc, v243, v244
	s_nop 1
	v_cndmask_b32_e32 v246, v242, v243, vcc
	v_lshlrev_b32_e32 v246, 2, v246
	ds_bpermute_b32 v246, v246, v245
	s_waitcnt lgkmcnt(0)
	v_max3_f32 v245, v98, v245, v246
	v_pk_add_f32 v[48:49], v[48:49], v[244:245] op_sel:[0,1] op_sel_hi:[1,1] neg_lo:[0,1] neg_hi:[0,1]
	v_exp_f32_e32 v246, v48
	v_exp_f32_e32 v247, v49
	v_pk_add_f32 v[50:51], v[50:51], v[244:245] op_sel:[0,1] op_sel_hi:[1,1] neg_lo:[0,1] neg_hi:[0,1]
	v_exp_f32_e32 v248, v50
	v_exp_f32_e32 v249, v51
	v_pk_add_f32 v[52:53], v[52:53], v[244:245] op_sel:[0,1] op_sel_hi:[1,1] neg_lo:[0,1] neg_hi:[0,1]
	v_exp_f32_e32 v52, v52
	v_exp_f32_e32 v53, v53
	v_pk_add_f32 v[54:55], v[54:55], v[244:245] op_sel:[0,1] op_sel_hi:[1,1] neg_lo:[0,1] neg_hi:[0,1]
	v_exp_f32_e32 v54, v54
	v_exp_f32_e32 v55, v55
	v_pk_add_f32 v[56:57], v[56:57], v[244:245] op_sel:[0,1] op_sel_hi:[1,1] neg_lo:[0,1] neg_hi:[0,1]
	v_exp_f32_e32 v56, v56
	v_exp_f32_e32 v57, v57
	v_pk_add_f32 v[58:59], v[58:59], v[244:245] op_sel:[0,1] op_sel_hi:[1,1] neg_lo:[0,1] neg_hi:[0,1]
	v_sub_f32_e32 v98, v98, v245
	v_exp_f32_e32 v58, v58
	v_exp_f32_e32 v98, v98
	v_exp_f32_e32 v59, v59
	v_pk_add_f32 v[60:61], v[60:61], v[244:245] op_sel:[0,1] op_sel_hi:[1,1] neg_lo:[0,1] neg_hi:[0,1]
	v_exp_f32_e32 v60, v60
	v_exp_f32_e32 v61, v61
	v_pk_add_f32 v[62:63], v[62:63], v[244:245] op_sel:[0,1] op_sel_hi:[1,1] neg_lo:[0,1] neg_hi:[0,1]
	v_exp_f32_e32 v62, v62
	v_pk_mul_f32 v[16:17], v[16:17], v[98:99] op_sel_hi:[1,0]
	v_pk_mul_f32 v[0:1], v[0:1], v[98:99] op_sel_hi:[1,0]
	v_pk_mul_f32 v[18:19], v[18:19], v[98:99] op_sel_hi:[1,0]
	v_pk_mul_f32 v[2:3], v[2:3], v[98:99] op_sel_hi:[1,0]
	v_pk_mul_f32 v[20:21], v[20:21], v[98:99] op_sel_hi:[1,0]
	v_pk_mul_f32 v[4:5], v[4:5], v[98:99] op_sel_hi:[1,0]
	v_pk_mul_f32 v[22:23], v[22:23], v[98:99] op_sel_hi:[1,0]
	v_pk_mul_f32 v[6:7], v[6:7], v[98:99] op_sel_hi:[1,0]
	v_pk_mul_f32 v[24:25], v[24:25], v[98:99] op_sel_hi:[1,0]
	v_pk_mul_f32 v[8:9], v[8:9], v[98:99] op_sel_hi:[1,0]
	v_pk_mul_f32 v[26:27], v[26:27], v[98:99] op_sel_hi:[1,0]
	v_pk_mul_f32 v[10:11], v[10:11], v[98:99] op_sel_hi:[1,0]
	v_pk_mul_f32 v[28:29], v[28:29], v[98:99] op_sel_hi:[1,0]
	v_pk_mul_f32 v[12:13], v[12:13], v[98:99] op_sel_hi:[1,0]
	v_pk_mul_f32 v[30:31], v[30:31], v[98:99] op_sel_hi:[1,0]
	v_pk_mul_f32 v[14:15], v[14:15], v[98:99] op_sel_hi:[1,0]
	v_exp_f32_e32 v63, v63
	v_cvt_pk_bf16_f32 v48, v246, v247
	v_cvt_pk_bf16_f32 v49, v248, v249
	v_cvt_pk_bf16_f32 v50, v52, v53
	v_cvt_pk_bf16_f32 v51, v54, v55
	v_pk_add_f32 v[32:33], v[32:33], v[244:245] op_sel:[0,1] op_sel_hi:[1,1] neg_lo:[0,1] neg_hi:[0,1]
	v_fmac_f32_e32 v246, v97, v98
	v_mfma_f32_32x32x16_bf16 v[16:31], v[160:163], v[48:51], v[16:31]
	v_mov_b32_e32 v98, v245
	v_mfma_f32_32x32x16_bf16 v[0:15], v[156:159], v[48:51], v[0:15]
	v_cvt_pk_bf16_f32 v48, v56, v57
	v_cvt_pk_bf16_f32 v49, v58, v59
	v_cvt_pk_bf16_f32 v50, v60, v61
	v_cvt_pk_bf16_f32 v51, v62, v63
	s_nop 1
	v_mfma_f32_32x32x16_bf16 v[16:31], v[148:151], v[48:51], v[16:31]
	v_mfma_f32_32x32x16_bf16 v[0:15], v[152:155], v[48:51], v[0:15]
	v_exp_f32_e32 v48, v32
	v_exp_f32_e32 v49, v33
	v_pk_add_f32 v[34:35], v[34:35], v[244:245] op_sel:[0,1] op_sel_hi:[1,1] neg_lo:[0,1] neg_hi:[0,1]
	v_exp_f32_e32 v50, v34
	v_exp_f32_e32 v51, v35
	v_pk_add_f32 v[36:37], v[36:37], v[244:245] op_sel:[0,1] op_sel_hi:[1,1] neg_lo:[0,1] neg_hi:[0,1]
	v_exp_f32_e32 v36, v36
	v_exp_f32_e32 v37, v37
	v_pk_add_f32 v[38:39], v[38:39], v[244:245] op_sel:[0,1] op_sel_hi:[1,1] neg_lo:[0,1] neg_hi:[0,1]
	v_exp_f32_e32 v38, v38
	v_exp_f32_e32 v39, v39
	v_pk_add_f32 v[40:41], v[40:41], v[244:245] op_sel:[0,1] op_sel_hi:[1,1] neg_lo:[0,1] neg_hi:[0,1]
	v_exp_f32_e32 v40, v40
	v_exp_f32_e32 v41, v41
	v_pk_add_f32 v[42:43], v[42:43], v[244:245] op_sel:[0,1] op_sel_hi:[1,1] neg_lo:[0,1] neg_hi:[0,1]
	v_exp_f32_e32 v42, v42
	v_exp_f32_e32 v43, v43
	v_pk_add_f32 v[44:45], v[44:45], v[244:245] op_sel:[0,1] op_sel_hi:[1,1] neg_lo:[0,1] neg_hi:[0,1]
	v_exp_f32_e32 v44, v44
	v_exp_f32_e32 v45, v45
	v_pk_add_f32 v[46:47], v[46:47], v[244:245] op_sel:[0,1] op_sel_hi:[1,1] neg_lo:[0,1] neg_hi:[0,1]
	v_exp_f32_e32 v46, v46
	v_exp_f32_e32 v47, v47
	v_cvt_pk_bf16_f32 v32, v48, v49
	v_cvt_pk_bf16_f32 v33, v50, v51
	v_cvt_pk_bf16_f32 v34, v36, v37
	v_cvt_pk_bf16_f32 v35, v38, v39
	s_nop 1
	v_mfma_f32_32x32x16_bf16 v[16:31], v[144:147], v[32:35], v[16:31]
	v_mfma_f32_32x32x16_bf16 v[0:15], v[140:143], v[32:35], v[0:15]
	v_cvt_pk_bf16_f32 v32, v40, v41
	v_cvt_pk_bf16_f32 v33, v42, v43
	v_cvt_pk_bf16_f32 v34, v44, v45
	v_cvt_pk_bf16_f32 v35, v46, v47
	s_nop 1
	v_mfma_f32_32x32x16_bf16 v[16:31], v[136:139], v[32:35], v[16:31]
	v_mfma_f32_32x32x16_bf16 v[0:15], v[132:135], v[32:35], v[0:15]
	v_add_f32_e32 v32, v247, v246
	v_add_f32_e32 v32, v248, v32
	v_add_f32_e32 v32, v249, v32
	v_add_f32_e32 v32, v52, v32
	v_add_f32_e32 v32, v53, v32
	v_add_f32_e32 v32, v54, v32
	v_add_f32_e32 v32, v55, v32
	v_add_f32_e32 v32, v56, v32
	v_add_f32_e32 v32, v57, v32
	v_add_f32_e32 v32, v58, v32
	v_add_f32_e32 v32, v59, v32
	v_add_f32_e32 v32, v60, v32
	v_add_f32_e32 v32, v61, v32
	v_add_f32_e32 v32, v62, v32
	v_add_f32_e32 v32, v63, v32
	v_add_f32_e32 v32, v48, v32
	v_add_f32_e32 v32, v49, v32
	v_add_f32_e32 v32, v50, v32
	v_add_f32_e32 v32, v51, v32
	v_add_f32_e32 v32, v36, v32
	v_add_f32_e32 v32, v37, v32
	v_add_f32_e32 v32, v38, v32
	v_add_f32_e32 v32, v39, v32
	v_add_f32_e32 v32, v40, v32
	v_add_f32_e32 v32, v41, v32
	v_add_f32_e32 v32, v42, v32
	v_add_f32_e32 v32, v43, v32
	v_add_f32_e32 v32, v44, v32
	v_add_f32_e32 v32, v45, v32
	v_add_f32_e32 v32, v46, v32
	v_add_f32_e32 v97, v47, v32
	v_mov_b32_e32 v133, v242
.LBB0_847:
	ds_read_b128 v[32:35], v239 offset:18432
	ds_read_b128 v[48:51], v239 offset:18464
	ds_read_b128 v[52:55], v239 offset:18496
	ds_read_b128 v[56:59], v239 offset:18528
	v_cmp_lt_i32_e32 vcc, v243, v244
	s_waitcnt vmcnt(3) lgkmcnt(3)
	v_mfma_f32_32x32x16_bf16 v[32:47], v[32:35], v[128:131], 0
	v_add_u32_e32 v132, s86, v164
	s_add_i32 s33, s33, s83
	s_waitcnt vmcnt(2) lgkmcnt(2)
	v_mfma_f32_32x32x16_bf16 v[32:47], v[48:51], v[124:127], v[32:47]
	s_waitcnt vmcnt(1) lgkmcnt(1)
	v_mfma_f32_32x32x16_bf16 v[32:47], v[52:55], v[116:119], v[32:47]
	s_waitcnt vmcnt(0) lgkmcnt(0)
	v_mfma_f32_32x32x16_bf16 v[32:47], v[56:59], v[120:123], v[32:47]
	ds_read_b128 v[60:63], v216
	ds_read_b128 v[56:59], v216 offset:25088
	ds_read_b128 v[48:51], v217
	ds_read_b128 v[52:55], v217 offset:25088
	s_nop 7
	v_cndmask_b32_e64 v116, v32, v240, s[46:47]
	v_cndmask_b32_e64 v116, v116, v32, s[4:5]
	v_cndmask_b32_e64 v117, v240, v33, s[4:5]
	v_cndmask_b32_e64 v34, v34, v240, s[48:49]
	v_cndmask_b32_e64 v35, v35, v240, s[50:51]
	v_max3_f32 v32, v116, s84, v117
	v_cndmask_b32_e64 v36, v36, v240, s[52:53]
	v_cndmask_b32_e64 v37, v37, v240, s[54:55]
	v_max3_f32 v32, v32, v34, v35
	v_cndmask_b32_e64 v38, v38, v240, s[56:57]
	v_cndmask_b32_e64 v39, v39, v240, s[58:59]
	v_max3_f32 v32, v32, v36, v37
	v_cndmask_b32_e64 v40, v40, v240, s[60:61]
	v_cndmask_b32_e64 v41, v41, v240, s[62:63]
	v_max3_f32 v32, v32, v38, v39
	v_cndmask_b32_e64 v42, v42, v240, s[64:65]
	v_cndmask_b32_e64 v43, v43, v240, s[66:67]
	v_max3_f32 v32, v32, v40, v41
	v_cndmask_b32_e64 v44, v44, v240, s[68:69]
	v_cndmask_b32_e64 v45, v45, v240, s[70:71]
	v_max3_f32 v32, v32, v42, v43
	v_cndmask_b32_e64 v46, v46, v240, s[72:73]
	v_cndmask_b32_e64 v47, v47, v240, s[74:75]
	v_max3_f32 v32, v32, v44, v45
	v_cndmask_b32_e32 v33, v133, v243, vcc
	v_max3_f32 v32, v32, v46, v47
	v_lshlrev_b32_e32 v118, 2, v33
	ds_bpermute_b32 v33, v118, v32
	s_waitcnt lgkmcnt(0)
	v_max3_f32 v33, v98, v32, v33
	v_pk_add_f32 v[34:35], v[34:35], v[32:33] op_sel:[0,1] op_sel_hi:[1,1] neg_lo:[0,1] neg_hi:[0,1]
	v_sub_f32_e32 v32, v98, v33
	v_sub_f32_e32 v98, v116, v33
	v_sub_f32_e32 v116, v117, v33
	v_exp_f32_e32 v117, v34
	v_exp_f32_e32 v119, v35
	v_pk_add_f32 v[36:37], v[36:37], v[32:33] op_sel:[0,1] op_sel_hi:[1,1] neg_lo:[0,1] neg_hi:[0,1]
	v_exp_f32_e32 v120, v36
	v_exp_f32_e32 v121, v37
	v_pk_add_f32 v[38:39], v[38:39], v[32:33] op_sel:[0,1] op_sel_hi:[1,1] neg_lo:[0,1] neg_hi:[0,1]
	v_exp_f32_e32 v38, v38
	v_exp_f32_e32 v39, v39
	v_pk_add_f32 v[40:41], v[40:41], v[32:33] op_sel:[0,1] op_sel_hi:[1,1] neg_lo:[0,1] neg_hi:[0,1]
	v_exp_f32_e32 v40, v40
	v_exp_f32_e32 v41, v41
	v_pk_add_f32 v[42:43], v[42:43], v[32:33] op_sel:[0,1] op_sel_hi:[1,1] neg_lo:[0,1] neg_hi:[0,1]
	v_exp_f32_e32 v42, v42
	v_exp_f32_e32 v32, v32
	v_exp_f32_e32 v98, v98
	v_exp_f32_e32 v116, v116
	v_exp_f32_e32 v43, v43
	v_pk_add_f32 v[44:45], v[44:45], v[32:33] op_sel:[0,1] op_sel_hi:[1,1] neg_lo:[0,1] neg_hi:[0,1]
	v_exp_f32_e32 v44, v44
	v_exp_f32_e32 v45, v45
	v_pk_add_f32 v[46:47], v[46:47], v[32:33] op_sel:[0,1] op_sel_hi:[1,1] neg_lo:[0,1] neg_hi:[0,1]
	v_exp_f32_e32 v46, v46
	v_exp_f32_e32 v47, v47
	v_cvt_pk_bf16_f32 v34, v98, v116
	v_fmac_f32_e32 v98, v97, v32
	v_pk_mul_f32 v[16:17], v[16:17], v[32:33] op_sel_hi:[1,0]
	v_pk_mul_f32 v[0:1], v[0:1], v[32:33] op_sel_hi:[1,0]
	v_pk_mul_f32 v[18:19], v[18:19], v[32:33] op_sel_hi:[1,0]
	v_pk_mul_f32 v[2:3], v[2:3], v[32:33] op_sel_hi:[1,0]
	v_pk_mul_f32 v[20:21], v[20:21], v[32:33] op_sel_hi:[1,0]
	v_pk_mul_f32 v[4:5], v[4:5], v[32:33] op_sel_hi:[1,0]
	v_pk_mul_f32 v[22:23], v[22:23], v[32:33] op_sel_hi:[1,0]
	v_pk_mul_f32 v[6:7], v[6:7], v[32:33] op_sel_hi:[1,0]
	v_pk_mul_f32 v[24:25], v[24:25], v[32:33] op_sel_hi:[1,0]
	v_pk_mul_f32 v[8:9], v[8:9], v[32:33] op_sel_hi:[1,0]
	v_pk_mul_f32 v[26:27], v[26:27], v[32:33] op_sel_hi:[1,0]
	v_pk_mul_f32 v[10:11], v[10:11], v[32:33] op_sel_hi:[1,0]
	v_pk_mul_f32 v[28:29], v[28:29], v[32:33] op_sel_hi:[1,0]
	v_pk_mul_f32 v[12:13], v[12:13], v[32:33] op_sel_hi:[1,0]
	v_pk_mul_f32 v[30:31], v[30:31], v[32:33] op_sel_hi:[1,0]
	v_pk_mul_f32 v[14:15], v[14:15], v[32:33] op_sel_hi:[1,0]
	v_add_f32_e32 v32, v116, v98
	v_add_f32_e32 v32, v117, v32
	v_add_f32_e32 v32, v119, v32
	v_add_f32_e32 v32, v120, v32
	v_add_f32_e32 v32, v121, v32
	v_add_f32_e32 v32, v38, v32
	v_cvt_pk_bf16_f32 v35, v117, v119
	v_cvt_pk_bf16_f32 v36, v120, v121
	v_cvt_pk_bf16_f32 v37, v38, v39
	v_add_f32_e32 v32, v39, v32
	v_add_f32_e32 v32, v40, v32
	v_mfma_f32_32x32x16_bf16 v[16:31], v[60:63], v[34:37], v[16:31]
	v_add_f32_e32 v32, v41, v32
	v_add_f32_e32 v32, v42, v32
	v_add_f32_e32 v32, v43, v32
	v_add_f32_e32 v32, v44, v32
	v_add_f32_e32 v32, v45, v32
	v_add_f32_e32 v32, v46, v32
	v_add_f32_e32 v32, v47, v32
	v_mfma_f32_32x32x16_bf16 v[0:15], v[56:59], v[34:37], v[0:15]
	v_cvt_pk_bf16_f32 v34, v40, v41
	v_cvt_pk_bf16_f32 v35, v42, v43
	v_cvt_pk_bf16_f32 v36, v44, v45
	v_cvt_pk_bf16_f32 v37, v46, v47
	s_nop 1
	v_mfma_f32_32x32x16_bf16 v[16:31], v[48:51], v[34:37], v[16:31]
	v_mfma_f32_32x32x16_bf16 v[0:15], v[52:55], v[34:37], v[0:15]
	ds_bpermute_b32 v34, v118, v32
	s_waitcnt lgkmcnt(0)
	v_add_f32_e32 v34, v32, v34
	v_div_scale_f32 v32, s[2:3], v34, v34, 1.0
	v_rcp_f32_e32 v35, v32
	s_lshr_b32 s2, 0x2000, s31
	s_add_i32 s2, s2, -1
	v_fma_f32 v36, -v32, v35, 1.0
	v_fmac_f32_e32 v35, v36, v35
	v_div_scale_f32 v36, vcc, 1.0, v34, 1.0
	v_mul_f32_e32 v37, v36, v35
	v_fma_f32 v38, -v32, v37, v36
	v_fmac_f32_e32 v37, v38, v35
	v_fma_f32 v32, -v32, v37, v36
	v_div_fmas_f32 v32, v32, v35, v37
	v_div_fixup_f32 v32, v32, v34, 1.0
	v_pk_mul_f32 v[16:17], v[16:17], v[32:33] op_sel_hi:[1,0]
	v_pk_mul_f32 v[0:1], v[0:1], v[32:33] op_sel_hi:[1,0]
	v_pk_mul_f32 v[18:19], v[18:19], v[32:33] op_sel_hi:[1,0]
	v_pk_mul_f32 v[2:3], v[2:3], v[32:33] op_sel_hi:[1,0]
	v_pk_mul_f32 v[20:21], v[20:21], v[32:33] op_sel_hi:[1,0]
	v_pk_mul_f32 v[4:5], v[4:5], v[32:33] op_sel_hi:[1,0]
	v_pk_mul_f32 v[22:23], v[22:23], v[32:33] op_sel_hi:[1,0]
	v_pk_mul_f32 v[6:7], v[6:7], v[32:33] op_sel_hi:[1,0]
	v_pk_mul_f32 v[24:25], v[24:25], v[32:33] op_sel_hi:[1,0]
	v_pk_mul_f32 v[8:9], v[8:9], v[32:33] op_sel_hi:[1,0]
	v_pk_mul_f32 v[26:27], v[26:27], v[32:33] op_sel_hi:[1,0]
	v_pk_mul_f32 v[10:11], v[10:11], v[32:33] op_sel_hi:[1,0]
	v_pk_mul_f32 v[28:29], v[28:29], v[32:33] op_sel_hi:[1,0]
	v_pk_mul_f32 v[12:13], v[12:13], v[32:33] op_sel_hi:[1,0]
	v_pk_mul_f32 v[30:31], v[30:31], v[32:33] op_sel_hi:[1,0]
	v_pk_mul_f32 v[14:15], v[14:15], v[32:33] op_sel_hi:[1,0]
	v_log_f32_e32 v32, v34
	v_and_b32_e32 v34, s2, v132
	s_sub_i32 s2, 13, s31
	v_lshlrev_b32_e32 v34, s31, v34
	v_lshrrev_b32_e32 v35, s2, v132
	v_cvt_pk_bf16_f32 v0, v0, v1
	v_cvt_pk_bf16_f32 v1, v2, v3
	v_cvt_pk_bf16_f32 v3, v6, v7
	v_or_b32_e32 v6, v220, v99
	v_or_b32_e32 v34, v34, v35
	v_lshlrev_b32_e32 v6, 2, v6
	ds_bpermute_b32 v6, v6, v34
	v_cvt_pk_bf16_f32 v16, v16, v17
	v_cvt_pk_bf16_f32 v17, v18, v19
	v_cvt_pk_bf16_f32 v18, v20, v21
	v_cvt_pk_bf16_f32 v19, v22, v23
	s_waitcnt lgkmcnt(0)
	v_ashrrev_i32_e32 v7, 31, v6
	ds_write2_b64 v237, v[16:17], v[18:19] offset1:2
	v_cvt_pk_bf16_f32 v16, v24, v25
	v_cvt_pk_bf16_f32 v17, v26, v27
	v_cvt_pk_bf16_f32 v18, v28, v29
	v_cvt_pk_bf16_f32 v19, v30, v31
	v_cvt_pk_bf16_f32 v2, v4, v5
	v_lshl_add_u64 v[4:5], s[76:77], 1, v[174:175]
	v_lshl_add_u64 v[6:7], s[34:35], 0, v[6:7]
	ds_write2_b64 v237, v[16:17], v[18:19] offset0:4 offset1:6
	ds_write2_b64 v237, v[0:1], v[2:3] offset0:8 offset1:10
	v_cvt_pk_bf16_f32 v0, v8, v9
	v_mad_u64_u32 v[8:9], s[2:3], v6, s82, v[4:5]
	v_or_b32_e32 v6, v221, v99
	v_cvt_pk_bf16_f32 v1, v10, v11
	v_cvt_pk_bf16_f32 v2, v12, v13
	v_cvt_pk_bf16_f32 v3, v14, v15
	v_lshlrev_b32_e32 v6, 2, v6
	ds_write2_b64 v237, v[0:1], v[2:3] offset0:12 offset1:14
	ds_bpermute_b32 v6, v6, v34
	s_waitcnt lgkmcnt(0)
	v_add_u32_e32 v0, v218, v219
	ds_read_b128 v[0:3], v0
	v_mad_i32_i24 v9, v7, s82, v9
	s_waitcnt lgkmcnt(1)
	v_ashrrev_i32_e32 v7, 31, v6
	v_lshl_add_u64 v[6:7], s[34:35], 0, v[6:7]
	v_ashrrev_i32_e32 v35, 31, v34
	s_waitcnt lgkmcnt(0)
	global_store_dwordx4 v[8:9], v[0:3], off
	v_mad_u64_u32 v[8:9], s[2:3], v6, s82, v[4:5]
	v_or_b32_e32 v6, v222, v99
	v_lshlrev_b32_e32 v6, 2, v6
	ds_bpermute_b32 v6, v6, v34
	ds_read_b128 v[0:3], v238
	v_mad_i32_i24 v9, v7, s82, v9
	s_ashr_i32 s31, s30, 31
	s_and_b64 vcc, exec, s[36:37]
	s_waitcnt lgkmcnt(1)
	v_ashrrev_i32_e32 v7, 31, v6
	v_lshl_add_u64 v[6:7], s[34:35], 0, v[6:7]
	s_waitcnt lgkmcnt(0)
	global_store_dwordx4 v[8:9], v[0:3], off
	v_mad_u64_u32 v[8:9], s[2:3], v6, s82, v[4:5]
	v_or_b32_e32 v6, v223, v99
	ds_read_b128 v[0:3], v238 offset:1152
	v_lshlrev_b32_e32 v6, 2, v6
	ds_bpermute_b32 v6, v6, v34
	v_mad_i32_i24 v9, v7, s82, v9
	s_waitcnt lgkmcnt(1)
	global_store_dwordx4 v[8:9], v[0:3], off
	ds_read_b128 v[0:3], v238 offset:2304
	s_waitcnt lgkmcnt(1)
	v_ashrrev_i32_e32 v7, 31, v6
	v_lshl_add_u64 v[6:7], s[34:35], 0, v[6:7]
	v_mad_u64_u32 v[4:5], s[2:3], v6, s82, v[4:5]
	v_mad_i32_i24 v5, v7, s82, v5
	s_waitcnt lgkmcnt(0)
	global_store_dwordx4 v[4:5], v[0:3], off
	v_add_f32_e32 v4, v33, v32
	s_nop 0
	v_lshl_add_u64 v[0:1], s[34:35], 0, v[34:35]
	v_mad_u64_u32 v[2:3], s[2:3], v0, 48, s[28:29]
	v_mad_i32_i24 v3, v1, 48, v3
	v_lshl_add_u64 v[0:1], s[30:31], 2, v[2:3]
	global_store_dword v[0:1], v4, off
	s_cbranch_vccnz .LBB0_883

.LBB0_877:
	v_max3_f32 v11, v0, s84, v20
	v_max3_f32 v11, v11, v21, v22
	v_max3_f32 v11, v11, v23, v5
	v_max3_f32 v11, v11, v6, v7
	v_max3_f32 v11, v11, v8, v9
	v_max3_f32 v11, v11, v10, v1
	v_max3_f32 v11, v11, v2, v3
	v_max3_f32 v11, v11, v4, v97
	v_max3_f32 v11, v11, v32, v33
	v_max3_f32 v11, v11, v34, v35
	v_max3_f32 v11, v11, v36, v37
	v_max3_f32 v11, v11, v38, v39
	v_and_b32_e32 v13, 64, v242
	v_max3_f32 v11, v11, v40, v41
	v_xor_b32_e32 v12, 32, v242
	v_add_u32_e32 v13, 64, v13
	v_max3_f32 v11, v11, v42, v43
	v_cmp_lt_i32_e32 vcc, v12, v13
	v_max3_f32 v11, v11, v44, v45
	v_max3_f32 v11, v11, v46, v47
	v_cndmask_b32_e32 v12, v242, v12, vcc
	v_lshlrev_b32_e32 v12, 2, v12
	ds_bpermute_b32 v12, v12, v11
	s_waitcnt lgkmcnt(0)
	v_max3_f32 v98, v11, v12, s84
	v_sub_f32_e32 v0, v0, v98
	v_exp_f32_e32 v99, v0
	v_pk_add_f32 v[20:21], v[20:21], v[98:99] op_sel_hi:[1,0] neg_lo:[0,1] neg_hi:[0,1]
	v_exp_f32_e32 v144, v20
	v_exp_f32_e32 v145, v21
	v_pk_add_f32 v[22:23], v[22:23], v[98:99] op_sel_hi:[1,0] neg_lo:[0,1] neg_hi:[0,1]
	v_exp_f32_e32 v146, v22
	v_exp_f32_e32 v147, v23
	v_pk_add_f32 v[4:5], v[4:5], v[98:99] op_sel_hi:[1,0] neg_lo:[0,1] neg_hi:[0,1]
	v_exp_f32_e32 v148, v5
	v_pk_add_f32 v[6:7], v[6:7], v[98:99] op_sel_hi:[1,0] neg_lo:[0,1] neg_hi:[0,1]
	v_exp_f32_e32 v149, v6
	v_exp_f32_e32 v150, v7
	v_pk_add_f32 v[8:9], v[8:9], v[98:99] op_sel_hi:[1,0] neg_lo:[0,1] neg_hi:[0,1]
	v_exp_f32_e32 v151, v8
	v_exp_f32_e32 v152, v9
	v_sub_f32_e32 v0, v10, v98
	v_cvt_pk_bf16_f32 v6, v99, v144
	v_cvt_pk_bf16_f32 v7, v145, v146
	v_cvt_pk_bf16_f32 v8, v147, v148
	v_cvt_pk_bf16_f32 v9, v149, v150
	v_exp_f32_e32 v153, v0
	v_sub_f32_e32 v0, v1, v98
	v_mfma_f32_32x32x16_bf16 v[16:31], v[16:19], v[6:9], 0
	v_exp_f32_e32 v154, v0
	v_pk_add_f32 v[2:3], v[2:3], v[98:99] op_sel_hi:[1,0] neg_lo:[0,1] neg_hi:[0,1]
	v_exp_f32_e32 v155, v2
	v_sub_f32_e32 v97, v97, v98
	v_exp_f32_e32 v156, v3
	v_exp_f32_e32 v157, v4
	v_exp_f32_e32 v97, v97
	v_mfma_f32_32x32x16_bf16 v[0:15], v[140:143], v[6:9], 0
	v_cvt_pk_bf16_f32 v140, v151, v152
	v_cvt_pk_bf16_f32 v141, v153, v154
	v_cvt_pk_bf16_f32 v142, v155, v156
	v_cvt_pk_bf16_f32 v143, v157, v97
	v_pk_add_f32 v[32:33], v[32:33], v[98:99] op_sel_hi:[1,0] neg_lo:[0,1] neg_hi:[0,1]
	v_pk_add_f32 v[42:43], v[42:43], v[98:99] op_sel_hi:[1,0] neg_lo:[0,1] neg_hi:[0,1]
	v_pk_add_f32 v[44:45], v[44:45], v[98:99] op_sel_hi:[1,0] neg_lo:[0,1] neg_hi:[0,1]
	v_mfma_f32_32x32x16_bf16 v[16:31], v[132:135], v[140:143], v[16:31]
	v_exp_f32_e32 v132, v32
	v_exp_f32_e32 v133, v33
	v_pk_add_f32 v[34:35], v[34:35], v[98:99] op_sel_hi:[1,0] neg_lo:[0,1] neg_hi:[0,1]
	v_exp_f32_e32 v134, v34
	v_exp_f32_e32 v135, v35
	v_pk_add_f32 v[36:37], v[36:37], v[98:99] op_sel_hi:[1,0] neg_lo:[0,1] neg_hi:[0,1]
	v_exp_f32_e32 v36, v36
	v_exp_f32_e32 v37, v37
	v_pk_add_f32 v[38:39], v[38:39], v[98:99] op_sel_hi:[1,0] neg_lo:[0,1] neg_hi:[0,1]
	v_mfma_f32_32x32x16_bf16 v[0:15], v[136:139], v[140:143], v[0:15]
	v_exp_f32_e32 v38, v38
	v_exp_f32_e32 v39, v39
	v_pk_add_f32 v[40:41], v[40:41], v[98:99] op_sel_hi:[1,0] neg_lo:[0,1] neg_hi:[0,1]
	v_exp_f32_e32 v40, v40
	v_exp_f32_e32 v41, v41
	v_exp_f32_e32 v42, v42
	v_cvt_pk_bf16_f32 v32, v132, v133
	v_cvt_pk_bf16_f32 v33, v134, v135
	v_cvt_pk_bf16_f32 v34, v36, v37
	v_cvt_pk_bf16_f32 v35, v38, v39
	v_pk_add_f32 v[46:47], v[46:47], v[98:99] op_sel_hi:[1,0] neg_lo:[0,1] neg_hi:[0,1]
	s_nop 0
	v_mfma_f32_32x32x16_bf16 v[16:31], v[60:63], v[32:35], v[16:31]
	v_exp_f32_e32 v43, v43
	v_exp_f32_e32 v44, v44
	v_exp_f32_e32 v45, v45
	v_exp_f32_e32 v46, v46
	v_mfma_f32_32x32x16_bf16 v[0:15], v[56:59], v[32:35], v[0:15]
	v_exp_f32_e32 v47, v47
	v_cvt_pk_bf16_f32 v32, v40, v41
	v_cvt_pk_bf16_f32 v33, v42, v43
	v_cvt_pk_bf16_f32 v34, v44, v45
	v_cvt_pk_bf16_f32 v35, v46, v47
	s_nop 1
	v_mfma_f32_32x32x16_bf16 v[16:31], v[52:55], v[32:35], v[16:31]
	v_sub_f32_e32 v52, 0xff800000, v98
	v_exp_f32_e32 v52, v52
	s_nop 0
	v_fmac_f32_e32 v99, 0, v52
	v_mfma_f32_32x32x16_bf16 v[0:15], v[48:51], v[32:35], v[0:15]
	v_add_f32_e32 v32, v144, v99
	v_add_f32_e32 v32, v145, v32
	v_add_f32_e32 v32, v146, v32
	v_add_f32_e32 v32, v147, v32
	v_add_f32_e32 v32, v148, v32
	v_add_f32_e32 v32, v149, v32
	v_add_f32_e32 v32, v150, v32
	v_add_f32_e32 v32, v151, v32
	v_add_f32_e32 v32, v152, v32
	v_add_f32_e32 v32, v153, v32
	v_add_f32_e32 v32, v154, v32
	v_add_f32_e32 v32, v155, v32
	v_add_f32_e32 v32, v156, v32
	v_add_f32_e32 v32, v157, v32
	v_add_f32_e32 v32, v97, v32
	v_add_f32_e32 v32, v132, v32
	v_add_f32_e32 v32, v133, v32
	v_add_f32_e32 v32, v134, v32
	v_add_f32_e32 v32, v135, v32
	v_add_f32_e32 v32, v36, v32
	v_add_f32_e32 v32, v37, v32
	v_add_f32_e32 v32, v38, v32
	v_add_f32_e32 v32, v39, v32
	v_add_f32_e32 v32, v40, v32
	v_add_f32_e32 v32, v41, v32
	v_add_f32_e32 v32, v42, v32
	v_add_f32_e32 v32, v43, v32
	v_add_f32_e32 v32, v44, v32
	v_add_f32_e32 v32, v45, v32
	v_add_f32_e32 v32, v46, v32
	v_add_f32_e32 v97, v47, v32
	s_or_b64 s[80:81], s[8:9], s[2:3]
	s_mov_b64 s[2:3], -1
	s_and_b64 vcc, exec, s[80:81]
	s_cbranch_vccnz .LBB0_880
	s_branch .LBB0_879
